# gMLP loop rewritten: tr-read A fragments, cross-unit prefetch, coalesced W loads via per-wave LDS, permuted M-tiles for 32B-contiguous gate loads and stores
# speedup vs baseline: 1.0021x; 1.0021x over previous
.Lgm_keep:
	v_lshrrev_b32_e32 v129, 4, v233
	v_bfe_u32 v128, v233, 2, 2
	v_mul_u32_u24_e32 v129, 0x480, v129
	v_mul_u32_u24_e32 v128, 0x90, v128
	v_add_u32_e32 v129, v129, v128
	v_and_b32_e32 v128, 3, v233
	v_lshl_add_u32 v129, v128, 5, v129
	v_lshlrev_b32_e32 v196, 2, v22
	v_mov_b32_e32 v197, 0
	v_lshrrev_b32_e32 v128, 5, v233
	v_and_b32_e32 v204, 31, v233
	s_mul_i32 s16, s3, 4352
	s_lshl_b32 s6, s3, 4
	s_addk_i32 s16, 18432
	v_mul_u32_u24_e32 v202, 272, v128
	v_add_u32_e32 v206, s6, v128
	v_lshl_add_u32 v202, v204, 3, v202
	v_lshlrev_b32_e32 v206, 9, v206
	v_add_u32_e32 v202, s16, v202
	v_lshl_add_u32 v206, v204, 4, v206
	v_and_b32_e32 v204, 15, v233
	v_lshrrev_b32_e32 v128, 4, v233
	v_mul_u32_u24_e32 v203, 272, v204
	v_mov_b32_e32 v207, 0
	v_lshl_add_u32 v203, v128, 4, v203
	v_lshl_add_u64 v[198:199], v[130:131], 0, v[206:207]
	v_add_u32_e32 v203, s16, v203
	v_mov_b32_e32 v206, 0x1000
	s_nop 0
	v_lshl_add_u64 v[200:201], v[198:199], 0, v[206:207]
	s_lshl_b32 s6, s15, 7
	s_and_b32 s6, s6, 0x180
	s_or_b32 s80, s6, s9
	s_and_b32 s16, s14, 0xffffff80
	s_mov_b32 s7, s81
	v_mov_b32_e32 v186, s80
	v_add_u32_e32 v190, s16, v36
	v_lshlrev_b32_e32 v186, 9, v186
	v_ashrrev_i32_e32 v191, 31, v190
	v_mov_b32_e32 v187, 0
	v_add_u32_e32 v194, s16, v18
	v_lshlrev_b64 v[190:191], 9, v[190:191]
	v_ashrrev_i32_e32 v195, 31, v194
	v_lshl_add_u64 v[190:191], s[0:1], 0, v[190:191]
	v_lshl_add_u64 v[188:189], v[198:199], 0, v[186:187]
	v_lshl_add_u64 v[190:191], v[190:191], 0, s[6:7]
	v_add_u32_e32 v192, s80, v18
	v_lshl_add_u64 v[190:191], v[190:191], 0, v[0:1]
	v_ashrrev_i32_e32 v193, 31, v192
	v_lshl_add_u64 v[186:187], v[200:201], 0, v[186:187]
	global_load_dwordx4 v[134:137], v[190:191], off offset:16
	global_load_dwordx4 v[138:141], v[190:191], off
	global_load_dwordx4 v[142:145], v[188:189], off
	global_load_dwordx4 v[146:149], v[188:189], off offset:1024
	global_load_dwordx4 v[150:153], v[188:189], off offset:2048
	global_load_dwordx4 v[154:157], v[188:189], off offset:3072
	global_load_dwordx4 v[158:161], v[186:187], off
	global_load_dwordx4 v[162:165], v[186:187], off offset:1024
	global_load_dwordx4 v[166:169], v[186:187], off offset:2048
	global_load_dwordx4 v[170:173], v[186:187], off offset:3072
	v_lshl_add_u64 v[192:193], v[192:193], 2, v[132:133]
	v_lshlrev_b64 v[194:195], 9, v[194:195]
	global_load_dword v174, v[192:193], off
	v_lshl_add_u64 v[194:195], s[4:5], 0, v[194:195]
	s_nop 0
	v_lshl_add_u64 v[194:195], v[194:195], 0, s[6:7]
	s_nop 0
	v_lshl_add_u64 v[194:195], v[194:195], 0, v[196:197]
	global_load_dwordx4 v[176:179], v[194:195], off
	global_load_dwordx4 v[180:183], v[194:195], off offset:16
	s_waitcnt vmcnt(0)
	s_branch .Lgm_top2

.Lgm_top2:
	s_lshl_b32 s6, s15, 7
	s_and_b32 s16, s14, 0xffffff80
	s_and_b32 s6, s6, 0x180
	v_add_u32_e32 v34, s16, v18
	v_ashrrev_i32_e32 v35, 31, v34
	ds_write_b128 v37, v[138:141]
	ds_write_b128 v37, v[134:137] offset:16
	v_cvt_pk_bf16_f32 v204, v142, v143
	v_cvt_pk_bf16_f32 v205, v144, v145
	ds_write_b64 v202, v[204:205]
	v_cvt_pk_bf16_f32 v206, v146, v147
	v_cvt_pk_bf16_f32 v207, v148, v149
	ds_write_b64 v202, v[206:207] offset:544
	v_cvt_pk_bf16_f32 v204, v150, v151
	v_cvt_pk_bf16_f32 v205, v152, v153
	ds_write_b64 v202, v[204:205] offset:1088
	v_cvt_pk_bf16_f32 v206, v154, v155
	v_cvt_pk_bf16_f32 v207, v156, v157
	ds_write_b64 v202, v[206:207] offset:1632
	v_cvt_pk_bf16_f32 v204, v158, v159
	v_cvt_pk_bf16_f32 v205, v160, v161
	ds_write_b64 v202, v[204:205] offset:2176
	v_cvt_pk_bf16_f32 v206, v162, v163
	v_cvt_pk_bf16_f32 v207, v164, v165
	ds_write_b64 v202, v[206:207] offset:2720
	v_cvt_pk_bf16_f32 v204, v166, v167
	v_cvt_pk_bf16_f32 v205, v168, v169
	ds_write_b64 v202, v[204:205] offset:3264
	v_cvt_pk_bf16_f32 v206, v170, v171
	v_cvt_pk_bf16_f32 v207, v172, v173
	ds_write_b64 v202, v[206:207] offset:3808
	v_lshlrev_b64 v[30:31], 11, v[34:35]
	v_or_b32_e32 v34, s6, v196
	v_mov_b32_e32 v35, v1
	v_lshl_add_u64 v[30:31], s[12:13], 0, v[30:31]
	v_mov_b32_e32 v39, v174
	v_lshl_add_u64 v[62:63], v[30:31], 0, v[34:35]
	v_mov_b32_e32 v60, v176
	v_mov_b32_e32 v61, v177
	v_mov_b32_e32 v28, v178
	v_mov_b32_e32 v29, v179
	v_mov_b32_e32 v26, v180
	v_mov_b32_e32 v27, v181
	v_mov_b32_e32 v24, v182
	v_mov_b32_e32 v25, v183
	ds_read_b128 v[14:17], v203
	ds_read_b128 v[10:13], v203 offset:64
	ds_read_b128 v[6:9], v203 offset:128
	ds_read_b128 v[2:5], v203 offset:192
	s_waitcnt lgkmcnt(0)
	s_barrier
	ds_read_b64_tr_b16 v[64:65], v129
	ds_read_b64_tr_b16 v[66:67], v129 offset:576
	ds_read_b64_tr_b16 v[68:69], v129 offset:4608
	ds_read_b64_tr_b16 v[70:71], v129 offset:5184
	ds_read_b64_tr_b16 v[72:73], v129 offset:9216
	ds_read_b64_tr_b16 v[74:75], v129 offset:9792
	ds_read_b64_tr_b16 v[76:77], v129 offset:13824
	ds_read_b64_tr_b16 v[78:79], v129 offset:14400
	ds_read_b64_tr_b16 v[80:81], v129 offset:8
	ds_read_b64_tr_b16 v[82:83], v129 offset:584
	ds_read_b64_tr_b16 v[84:85], v129 offset:4616
	ds_read_b64_tr_b16 v[86:87], v129 offset:5192
	s_add_i32 s15, s15, s100
	s_add_i32 s14, s14, s101
	s_cmp_ge_i32 s15, s8
	s_cbranch_scc1 .Lgm_nopf
	s_lshl_b32 s6, s15, 7
	s_and_b32 s6, s6, 0x180
	s_or_b32 s80, s6, s9
	s_and_b32 s16, s14, 0xffffff80
	s_mov_b32 s7, s81
	v_mov_b32_e32 v186, s80
	v_add_u32_e32 v190, s16, v36
	v_lshlrev_b32_e32 v186, 9, v186
	v_ashrrev_i32_e32 v191, 31, v190
	v_mov_b32_e32 v187, 0
	v_add_u32_e32 v194, s16, v18
	v_lshlrev_b64 v[190:191], 9, v[190:191]
	v_ashrrev_i32_e32 v195, 31, v194
	v_lshl_add_u64 v[190:191], s[0:1], 0, v[190:191]
	v_lshl_add_u64 v[188:189], v[198:199], 0, v[186:187]
	v_lshl_add_u64 v[190:191], v[190:191], 0, s[6:7]
	v_add_u32_e32 v192, s80, v18
	v_lshl_add_u64 v[190:191], v[190:191], 0, v[0:1]
	v_ashrrev_i32_e32 v193, 31, v192
	v_lshl_add_u64 v[186:187], v[200:201], 0, v[186:187]
	global_load_dwordx4 v[134:137], v[190:191], off offset:16
	global_load_dwordx4 v[138:141], v[190:191], off
	global_load_dwordx4 v[142:145], v[188:189], off
	global_load_dwordx4 v[146:149], v[188:189], off offset:1024
	global_load_dwordx4 v[150:153], v[188:189], off offset:2048
	global_load_dwordx4 v[154:157], v[188:189], off offset:3072
	global_load_dwordx4 v[158:161], v[186:187], off
	global_load_dwordx4 v[162:165], v[186:187], off offset:1024
	global_load_dwordx4 v[166:169], v[186:187], off offset:2048
	global_load_dwordx4 v[170:173], v[186:187], off offset:3072
	v_lshl_add_u64 v[192:193], v[192:193], 2, v[132:133]
	v_lshlrev_b64 v[194:195], 9, v[194:195]
	global_load_dword v174, v[192:193], off
	v_lshl_add_u64 v[194:195], s[4:5], 0, v[194:195]
	s_nop 0
	v_lshl_add_u64 v[194:195], v[194:195], 0, s[6:7]
	s_nop 0
	v_lshl_add_u64 v[194:195], v[194:195], 0, v[196:197]
	global_load_dwordx4 v[176:179], v[194:195], off
	global_load_dwordx4 v[180:183], v[194:195], off offset:16
.Lgm_nopf:
	s_waitcnt lgkmcnt(4)
	v_mfma_f32_16x16x32_bf16 v[40:43], v[64:67], v[14:17], 0
	v_mfma_f32_16x16x32_bf16 v[40:43], v[68:71], v[10:13], v[40:43]
	v_mfma_f32_16x16x32_bf16 v[40:43], v[72:75], v[6:9], v[40:43]
	v_mfma_f32_16x16x32_bf16 v[40:43], v[76:79], v[2:5], v[40:43]
	ds_read_b64_tr_b16 v[88:89], v129 offset:9224
	ds_read_b64_tr_b16 v[90:91], v129 offset:9800
	ds_read_b64_tr_b16 v[92:93], v129 offset:13832
	ds_read_b64_tr_b16 v[94:95], v129 offset:14408
	ds_read_b64_tr_b16 v[96:97], v129 offset:16
	ds_read_b64_tr_b16 v[98:99], v129 offset:592
	ds_read_b64_tr_b16 v[100:101], v129 offset:4624
	ds_read_b64_tr_b16 v[102:103], v129 offset:5200
	s_waitcnt lgkmcnt(4)
	v_mfma_f32_16x16x32_bf16 v[44:47], v[80:83], v[14:17], 0
	v_mfma_f32_16x16x32_bf16 v[44:47], v[84:87], v[10:13], v[44:47]
	v_mfma_f32_16x16x32_bf16 v[44:47], v[88:91], v[6:9], v[44:47]
	v_mfma_f32_16x16x32_bf16 v[44:47], v[92:95], v[2:5], v[44:47]
	ds_read_b64_tr_b16 v[104:105], v129 offset:9232
	ds_read_b64_tr_b16 v[106:107], v129 offset:9808
	ds_read_b64_tr_b16 v[108:109], v129 offset:13840
	ds_read_b64_tr_b16 v[110:111], v129 offset:14416
	ds_read_b64_tr_b16 v[112:113], v129 offset:24
	ds_read_b64_tr_b16 v[114:115], v129 offset:600
	ds_read_b64_tr_b16 v[116:117], v129 offset:4632
	ds_read_b64_tr_b16 v[118:119], v129 offset:5208
	v_lshlrev_b32_e32 v184, 16, v60
	v_add_f32_e32 v40, v39, v40
	v_and_b32_e32 v185, 0xffff0000, v60
	v_add_f32_e32 v41, v39, v41
	v_lshlrev_b32_e32 v208, 16, v61
	v_add_f32_e32 v42, v39, v42
	v_and_b32_e32 v209, 0xffff0000, v61
	v_add_f32_e32 v43, v39, v43
	v_mul_f32_e32 v184, v40, v184
	v_mul_f32_e32 v185, v41, v185
	v_mul_f32_e32 v208, v42, v208
	v_mul_f32_e32 v209, v43, v209
	v_cvt_pk_bf16_f32 v56, v184, v185
	v_cvt_pk_bf16_f32 v57, v208, v209
	s_waitcnt lgkmcnt(4)
	v_mfma_f32_16x16x32_bf16 v[48:51], v[96:99], v[14:17], 0
	v_mfma_f32_16x16x32_bf16 v[48:51], v[100:103], v[10:13], v[48:51]
	v_mfma_f32_16x16x32_bf16 v[48:51], v[104:107], v[6:9], v[48:51]
	v_mfma_f32_16x16x32_bf16 v[48:51], v[108:111], v[2:5], v[48:51]
	ds_read_b64_tr_b16 v[120:121], v129 offset:9240
	ds_read_b64_tr_b16 v[122:123], v129 offset:9816
	ds_read_b64_tr_b16 v[124:125], v129 offset:13848
	ds_read_b64_tr_b16 v[126:127], v129 offset:14424
	v_lshlrev_b32_e32 v184, 16, v28
	v_add_f32_e32 v44, v39, v44
	v_and_b32_e32 v185, 0xffff0000, v28
	v_add_f32_e32 v45, v39, v45
	v_lshlrev_b32_e32 v208, 16, v29
	v_add_f32_e32 v46, v39, v46
	v_and_b32_e32 v209, 0xffff0000, v29
	v_add_f32_e32 v47, v39, v47
	v_mul_f32_e32 v184, v44, v184
	v_mul_f32_e32 v185, v45, v185
	v_mul_f32_e32 v208, v46, v208
	v_mul_f32_e32 v209, v47, v209
	v_cvt_pk_bf16_f32 v58, v184, v185
	v_cvt_pk_bf16_f32 v59, v208, v209
	global_store_dwordx4 v[62:63], v[56:59], off
	s_waitcnt lgkmcnt(0)
	v_mfma_f32_16x16x32_bf16 v[52:55], v[112:115], v[14:17], 0
	v_mfma_f32_16x16x32_bf16 v[52:55], v[116:119], v[10:13], v[52:55]
	v_mfma_f32_16x16x32_bf16 v[52:55], v[120:123], v[6:9], v[52:55]
	v_mfma_f32_16x16x32_bf16 v[52:55], v[124:127], v[2:5], v[52:55]
	v_lshlrev_b32_e32 v184, 16, v26
	v_add_f32_e32 v48, v39, v48
	v_and_b32_e32 v185, 0xffff0000, v26
	v_add_f32_e32 v49, v39, v49
	v_lshlrev_b32_e32 v208, 16, v27
	v_add_f32_e32 v50, v39, v50
	v_and_b32_e32 v209, 0xffff0000, v27
	v_add_f32_e32 v51, v39, v51
	v_mul_f32_e32 v184, v48, v184
	v_mul_f32_e32 v185, v49, v185
	v_mul_f32_e32 v208, v50, v208
	v_mul_f32_e32 v209, v51, v209
	v_cvt_pk_bf16_f32 v30, v184, v185
	v_cvt_pk_bf16_f32 v31, v208, v209
	s_nop 7
	v_lshlrev_b32_e32 v184, 16, v24
	v_add_f32_e32 v52, v39, v52
	v_and_b32_e32 v185, 0xffff0000, v24
	v_add_f32_e32 v53, v39, v53
	v_lshlrev_b32_e32 v208, 16, v25
	v_add_f32_e32 v54, v39, v54
	v_and_b32_e32 v209, 0xffff0000, v25
	v_add_f32_e32 v55, v39, v55
	v_mul_f32_e32 v184, v52, v184
	v_mul_f32_e32 v185, v53, v185
	v_mul_f32_e32 v208, v54, v208
	v_mul_f32_e32 v209, v55, v209
	v_cvt_pk_bf16_f32 v32, v184, v185
	v_cvt_pk_bf16_f32 v33, v208, v209
	global_store_dwordx4 v[62:63], v[30:33], off offset:16
	s_barrier
	s_cmp_ge_i32 s15, s8
	s_cbranch_scc0 .LBB0_968
